# s5_prompt: per-chunk input rows prefetched 8 chunks ahead through an LDS-DMA ring (was a 1-chunk register prefetch)
# speedup vs baseline: 1.0138x; 1.0138x over previous
.LBB0_457:
	s_or_b64 exec, exec, s[2:3]
	s_waitcnt vmcnt(8)
	v_mul_f32_e32 v43, v36, v39
	v_mul_f32_e32 v32, 0x3fb8aa3b, v43
	s_mov_b32 s2, 0x3fb8aa3b
	v_fma_f32 v33, v43, s2, -v32
	v_rndne_f32_e32 v34, v32
	v_fmac_f32_e32 v33, 0x32a5705f, v43
	v_sub_f32_e32 v32, v32, v34
	v_add_f32_e32 v32, v32, v33
	v_exp_f32_e32 v32, v32
	v_cvt_i32_f32_e32 v33, v34
	s_mov_b32 s2, 0xc2ce8ed0
	v_cmp_ngt_f32_e32 vcc, s2, v43
	s_mov_b32 s2, 0x42b17218
	v_ldexp_f32 v32, v32, v33
	v_cndmask_b32_e32 v32, 0, v32, vcc
	v_cmp_nlt_f32_e32 vcc, s2, v43
	s_brev_b32 s2, 1
	v_xor_b32_e32 v38, v38, v46
	v_cndmask_b32_e32 v33, v233, v32, vcc
	v_mul_f32_e32 v32, v41, v41
	v_fmamk_f32 v34, v32, 0xb94c1982, v224
	v_fmaak_f32 v34, v32, v34, 0xbe2aaa9d
	v_mul_f32_e32 v34, v32, v34
	v_fmac_f32_e32 v41, v41, v34
	v_fmamk_f32 v34, v32, 0x37d75334, v226
	v_fmaak_f32 v34, v32, v34, 0x3d2aabf7
	v_fmaak_f32 v34, v32, v34, 0xbf000004
	v_fma_f32 v32, v32, v34, 1.0
	v_and_b32_e32 v34, 1, v40
	v_cmp_eq_u32_e32 vcc, 0, v34
	v_lshlrev_b32_e32 v34, 30, v40
	s_ashr_i32 s35, s30, 6
	v_cndmask_b32_e64 v32, -v41, v32, vcc
	v_bitop3_b32 v32, v34, v32, s2 bitop3:0x6c
	v_mul_f32_e32 v34, v45, v45
	v_fmamk_f32 v39, v34, 0xb94c1982, v224
	v_fmaak_f32 v39, v34, v39, 0xbe2aaa9d
	v_mul_f32_e32 v39, v34, v39
	v_fmac_f32_e32 v45, v45, v39
	v_fmamk_f32 v39, v34, 0x37d75334, v226
	v_fmaak_f32 v39, v34, v39, 0x3d2aabf7
	v_fmaak_f32 v39, v34, v39, 0xbf000004
	v_fma_f32 v34, v34, v39, 1.0
	v_and_b32_e32 v39, 1, v44
	v_cmp_eq_u32_e64 s[8:9], 0, v39
	v_lshlrev_b32_e32 v39, 30, v44
	v_and_b32_e32 v39, 0x80000000, v39
	s_movk_i32 s2, 0x1f8
	v_cndmask_b32_e64 v34, v34, v45, s[8:9]
	v_xor_b32_e32 v38, v38, v39
	v_cmp_class_f32_e64 vcc, v46, s2
	v_xor_b32_e32 v34, v38, v34
	v_mov_b32_e32 v44, v37
	v_cndmask_b32_e32 v34, v236, v34, vcc
	v_cndmask_b32_e32 v35, v236, v32, vcc
	v_mul_f32_e32 v34, v33, v34
	v_fma_f32 v40, v33, v35, -1.0
	v_mov_b32_e32 v41, v34
	v_pk_mul_f32 v[38:39], v[36:37], v[36:37]
	v_pk_mul_f32 v[44:45], v[44:45], v[40:41] op_sel:[0,1] op_sel_hi:[0,0]
	v_pk_fma_f32 v[48:49], v[36:37], v[40:41], v[44:45]
	v_pk_fma_f32 v[36:37], v[36:37], v[40:41], v[44:45] op_sel_hi:[0,1,1] neg_lo:[0,0,1] neg_hi:[0,0,1]
	v_pk_add_f32 v[38:39], v[38:39], v[38:39] op_sel:[0,1] op_sel_hi:[0,1]
	v_mul_f32_e32 v32, v33, v35
	v_div_scale_f32 v33, s[2:3], v39, v39, v37
	v_rcp_f32_e32 v35, v33
	s_lshl_b32 s20, s35, 9
	s_ashr_i32 s17, s31, 4
	s_add_i32 s8, s20, 0x200
	v_fma_f32 v36, -v33, v35, 1.0
	v_fmac_f32_e32 v35, v36, v35
	v_div_scale_f32 v36, vcc, v37, v39, v37
	v_mul_f32_e32 v40, v36, v35
	v_fma_f32 v41, -v33, v40, v36
	v_fmac_f32_e32 v40, v41, v35
	v_fma_f32 v33, -v33, v40, v36
	v_div_fmas_f32 v33, v33, v35, v40
	v_div_fixup_f32 v41, v33, v39, v37
	v_div_scale_f32 v33, s[2:3], v38, v38, v48
	v_rcp_f32_e32 v35, v33
	s_cmp_eq_u32 s35, 3
	s_cselect_b64 s[2:3], -1, 0
	s_and_b64 s[4:5], s[2:3], exec
	v_fma_f32 v36, -v33, v35, 1.0
	v_fmac_f32_e32 v35, v36, v35
	v_div_scale_f32 v36, vcc, v48, v38, v48
	v_mul_f32_e32 v37, v36, v35
	v_fma_f32 v39, -v33, v37, v36
	v_fmac_f32_e32 v37, v39, v35
	v_fma_f32 v33, -v33, v37, v36
	v_div_fmas_f32 v33, v33, v35, v37
	v_div_fixup_f32 v40, v33, v38, v48
	s_waitcnt vmcnt(0)
	v_pk_mul_f32 v[38:39], v[28:29], v[40:41] op_sel:[0,1] op_sel_hi:[0,0]
	v_pk_fma_f32 v[36:37], v[24:25], v[40:41], v[38:39] neg_lo:[0,0,1] neg_hi:[0,0,1]
	v_pk_fma_f32 v[38:39], v[24:25], v[40:41], v[38:39] op_sel_hi:[0,1,1]
	v_mov_b32_e32 v37, v39
	v_pk_mul_f32 v[38:39], v[28:29], v[40:41] op_sel:[1,1] op_sel_hi:[1,0]
	v_mov_b32_e32 v28, v25
	v_pk_fma_f32 v[28:29], v[28:29], v[40:41], v[38:39] neg_lo:[0,0,1] neg_hi:[0,0,1]
	v_pk_fma_f32 v[24:25], v[24:25], v[40:41], v[38:39] op_sel:[1,0,0]
	v_pk_mul_f32 v[38:39], v[30:31], v[40:41] op_sel:[0,1] op_sel_hi:[0,0]
	v_mov_b32_e32 v29, v25
	v_pk_fma_f32 v[24:25], v[26:27], v[40:41], v[38:39] neg_lo:[0,0,1] neg_hi:[0,0,1]
	v_pk_fma_f32 v[38:39], v[26:27], v[40:41], v[38:39] op_sel_hi:[0,1,1]
	v_mov_b32_e32 v26, v31
	v_pk_mul_f32 v[30:31], v[26:27], v[40:41] op_sel:[0,1] op_sel_hi:[0,0]
	v_mov_b32_e32 v26, v27
	v_mov_b32_e32 v38, v27
	v_mov_b32_e32 v25, v39
	v_pk_fma_f32 v[26:27], v[26:27], v[40:41], v[30:31] neg_lo:[0,0,1] neg_hi:[0,0,1]
	v_pk_fma_f32 v[30:31], v[38:39], v[40:41], v[30:31] op_sel_hi:[0,1,1]
	v_pk_mul_f32 v[38:39], v[40:41], v[20:21] op_sel:[1,0] op_sel_hi:[0,0]
	v_mov_b32_e32 v27, v31
	v_pk_fma_f32 v[30:31], v[16:17], v[40:41], v[38:39] neg_lo:[0,0,1] neg_hi:[0,0,1]
	v_pk_fma_f32 v[38:39], v[16:17], v[40:41], v[38:39] op_sel_hi:[0,1,1]
	v_mov_b32_e32 v16, v21
	v_pk_mul_f32 v[20:21], v[40:41], v[16:17] op_sel:[1,0] op_sel_hi:[0,0]
	v_mov_b32_e32 v16, v17
	v_mov_b32_e32 v38, v17
	v_mov_b32_e32 v31, v39
	v_pk_fma_f32 v[16:17], v[16:17], v[40:41], v[20:21] neg_lo:[0,0,1] neg_hi:[0,0,1]
	v_pk_fma_f32 v[20:21], v[38:39], v[40:41], v[20:21] op_sel_hi:[0,1,1]
	v_pk_mul_f32 v[38:39], v[40:41], v[22:23] op_sel:[1,0] op_sel_hi:[0,0]
	v_mov_b32_e32 v17, v21
	v_pk_fma_f32 v[20:21], v[18:19], v[40:41], v[38:39] neg_lo:[0,0,1] neg_hi:[0,0,1]
	v_pk_fma_f32 v[38:39], v[18:19], v[40:41], v[38:39] op_sel_hi:[0,1,1]
	v_mov_b32_e32 v18, v23
	v_pk_mul_f32 v[22:23], v[40:41], v[18:19] op_sel:[1,0] op_sel_hi:[0,0]
	v_mov_b32_e32 v18, v19
	v_mov_b32_e32 v38, v19
	v_mov_b32_e32 v21, v39
	v_pk_fma_f32 v[18:19], v[18:19], v[40:41], v[22:23] neg_lo:[0,0,1] neg_hi:[0,0,1]
	v_pk_fma_f32 v[22:23], v[38:39], v[40:41], v[22:23] op_sel_hi:[0,1,1]
	v_pk_mul_f32 v[38:39], v[40:41], v[12:13] op_sel:[1,0] op_sel_hi:[0,0]
	v_mov_b32_e32 v19, v23
	v_pk_fma_f32 v[22:23], v[40:41], v[8:9], v[38:39] neg_lo:[0,0,1] neg_hi:[0,0,1]
	v_pk_fma_f32 v[38:39], v[40:41], v[8:9], v[38:39] op_sel_hi:[1,0,1]
	v_mov_b32_e32 v8, v13
	v_pk_mul_f32 v[12:13], v[40:41], v[8:9] op_sel:[1,0] op_sel_hi:[0,0]
	v_mov_b32_e32 v8, v9
	v_mov_b32_e32 v23, v39
	v_pk_fma_f32 v[38:39], v[40:41], v[8:9], v[12:13] op_sel_hi:[1,0,1]
	v_pk_fma_f32 v[8:9], v[40:41], v[8:9], v[12:13] op_sel_hi:[1,0,1] neg_lo:[0,0,1] neg_hi:[0,0,1]
	v_pk_mul_f32 v[12:13], v[40:41], v[14:15] op_sel:[1,0] op_sel_hi:[0,0]
	v_mov_b32_e32 v9, v39
	v_pk_fma_f32 v[38:39], v[40:41], v[10:11], v[12:13] op_sel_hi:[1,0,1]
	v_pk_fma_f32 v[12:13], v[40:41], v[10:11], v[12:13] op_sel_hi:[1,0,1] neg_lo:[0,0,1] neg_hi:[0,0,1]
	v_mov_b32_e32 v10, v15
	v_pk_mul_f32 v[14:15], v[40:41], v[10:11] op_sel:[1,0] op_sel_hi:[0,0]
	v_mov_b32_e32 v10, v11
	v_mov_b32_e32 v13, v39
	v_pk_fma_f32 v[38:39], v[40:41], v[10:11], v[14:15] op_sel_hi:[1,0,1]
	v_pk_fma_f32 v[10:11], v[40:41], v[10:11], v[14:15] op_sel_hi:[1,0,1] neg_lo:[0,0,1] neg_hi:[0,0,1]
	v_pk_mul_f32 v[14:15], v[40:41], v[4:5] op_sel:[1,0] op_sel_hi:[0,0]
	v_mov_b32_e32 v11, v39
	v_pk_fma_f32 v[38:39], v[40:41], v[0:1], v[14:15] op_sel_hi:[1,0,1]
	v_pk_fma_f32 v[14:15], v[40:41], v[0:1], v[14:15] op_sel_hi:[1,0,1] neg_lo:[0,0,1] neg_hi:[0,0,1]
	v_mov_b32_e32 v0, v5
	v_pk_mul_f32 v[4:5], v[40:41], v[0:1] op_sel:[1,0] op_sel_hi:[0,0]
	v_mov_b32_e32 v0, v1
	v_mov_b32_e32 v15, v39
	v_pk_fma_f32 v[38:39], v[40:41], v[0:1], v[4:5] op_sel_hi:[1,0,1]
	v_pk_fma_f32 v[4:5], v[40:41], v[0:1], v[4:5] op_sel_hi:[1,0,1] neg_lo:[0,0,1] neg_hi:[0,0,1]
	v_pk_mul_f32 v[0:1], v[40:41], v[6:7] op_sel:[1,0] op_sel_hi:[0,0]
	s_mul_i32 s34, s17, 0x810
	s_mul_i32 s4, s17, 0x912000
	v_mov_b32_e32 v5, v39
	v_pk_fma_f32 v[44:45], v[40:41], v[2:3], v[0:1] op_sel_hi:[1,0,1]
	v_pk_fma_f32 v[38:39], v[40:41], v[2:3], v[0:1] op_sel_hi:[1,0,1] neg_lo:[0,0,1] neg_hi:[0,0,1]
	v_mov_b32_e32 v0, v7
	s_cselect_b32 s21, 0x810, s8
	s_mul_hi_i32 s5, s34, 0x1200
	s_add_u32 s4, s50, s4
	v_pk_mul_f32 v[0:1], v[40:41], v[0:1] op_sel:[1,0] op_sel_hi:[0,0]
	v_mov_b32_e32 v2, v3
	s_addc_u32 s5, s51, s5
	s_lshl_b32 s8, s16, 5
	v_lshrrev_b32_e32 v47, 1, v52
	v_mov_b32_e32 v39, v45
	v_pk_fma_f32 v[44:45], v[40:41], v[2:3], v[0:1] op_sel_hi:[1,0,1]
	v_pk_fma_f32 v[6:7], v[40:41], v[2:3], v[0:1] op_sel_hi:[1,0,1] neg_lo:[0,0,1] neg_hi:[0,0,1]
	s_add_u32 s4, s4, s8
	v_mul_u32_u24_e32 v0, 0x900, v47
	v_lshlrev_b32_e32 v2, 3, v42
	s_addc_u32 s5, s5, 0
	v_lshlrev_b32_e32 v200, 1, v0
	v_and_b32_e32 v48, 8, v2
	v_lshl_add_u64 v[0:1], s[4:5], 0, v[200:201]
	v_lshlrev_b32_e32 v200, 1, v48
	v_lshl_add_u64 v[0:1], v[0:1], 0, v[200:201]
	s_mov_b64 s[4:5], 0x9919800
	v_mov_b32_e32 v7, v45
	s_mul_i32 s31, s35, 0x1240
	v_lshl_add_u64 v[40:41], v[0:1], 0, s[4:5]
	s_cmp_lt_i32 s35, 3
	v_cmp_gt_u32_e32 vcc, 16, v52
	s_cbranch_scc0 .LBB0_468
	v_mov_b32_e32 v200, v201
	v_mov_b64_e32 v[0:1], v[200:201]
	v_mov_b64_e32 v[2:3], v[200:201]
	s_and_saveexec_b64 s[4:5], vcc
	s_cbranch_execz .LBB0_460
	s_ashr_i32 s8, s30, 6
	s_lshl_b32 s8, s8, 11
	s_add_u32 m0, s8, 0x8000
	s_add_i32 s8, s20, 0
	v_mad_i64_i32 v[0:1], s[8:9], s8, v242, v[40:41]
	s_nop 0
	global_load_lds_dwordx4 v[0:1], off
	s_ashr_i32 s8, s30, 6
	s_lshl_b32 s8, s8, 11
	s_add_u32 m0, s8, 0x8100
	s_add_i32 s8, s20, 8
	v_mad_i64_i32 v[0:1], s[8:9], s8, v242, v[40:41]
	s_nop 0
	global_load_lds_dwordx4 v[0:1], off
	s_ashr_i32 s8, s30, 6
	s_lshl_b32 s8, s8, 11
	s_add_u32 m0, s8, 0x8200
	s_add_i32 s8, s20, 16
	v_mad_i64_i32 v[0:1], s[8:9], s8, v242, v[40:41]
	s_nop 0
	global_load_lds_dwordx4 v[0:1], off
	s_ashr_i32 s8, s30, 6
	s_lshl_b32 s8, s8, 11
	s_add_u32 m0, s8, 0x8300
	s_add_i32 s8, s20, 24
	v_mad_i64_i32 v[0:1], s[8:9], s8, v242, v[40:41]
	s_nop 0
	global_load_lds_dwordx4 v[0:1], off
	s_ashr_i32 s8, s30, 6
	s_lshl_b32 s8, s8, 11
	s_add_u32 m0, s8, 0x8400
	s_add_i32 s8, s20, 32
	v_mad_i64_i32 v[0:1], s[8:9], s8, v242, v[40:41]
	s_nop 0
	global_load_lds_dwordx4 v[0:1], off
	s_ashr_i32 s8, s30, 6
	s_lshl_b32 s8, s8, 11
	s_add_u32 m0, s8, 0x8500
	s_add_i32 s8, s20, 40
	v_mad_i64_i32 v[0:1], s[8:9], s8, v242, v[40:41]
	s_nop 0
	global_load_lds_dwordx4 v[0:1], off
	s_ashr_i32 s8, s30, 6
	s_lshl_b32 s8, s8, 11
	s_add_u32 m0, s8, 0x8600
	s_add_i32 s8, s20, 48
	v_mad_i64_i32 v[0:1], s[8:9], s8, v242, v[40:41]
	s_nop 0
	global_load_lds_dwordx4 v[0:1], off
	s_ashr_i32 s8, s30, 6
	s_lshl_b32 s8, s8, 11
	s_add_u32 m0, s8, 0x8700
	s_add_i32 s8, s20, 56
	v_mad_i64_i32 v[0:1], s[8:9], s8, v242, v[40:41]
	s_nop 0
	global_load_lds_dwordx4 v[0:1], off

.LBB0_461:
	s_and_saveexec_b64 s[4:5], vcc
	s_cbranch_execz .LBB0_464
	s_add_i32 s10, s9, 64
	s_cmp_ge_i32 s10, s21
	s_cbranch_scc1 .Ls5p1_drain
	s_waitcnt vmcnt(7)
	s_branch .Ls5p1_go

.Ls5p1_go:
	s_lshr_b32 s11, s9, 3
	s_and_b32 s11, s11, 7
	s_lshl_b32 s11, s11, 8
	s_ashr_i32 m0, s30, 6
	s_lshl_b32 m0, m0, 11
	s_add_u32 s11, s11, m0
	s_add_u32 s11, s11, 0x8000
	v_lshl_add_u32 v54, v52, 4, s11
	ds_read_b128 v[0:3], v54
	s_waitcnt lgkmcnt(0)
	v_lshlrev_b32_e32 v54, 16, v0
	v_and_b32_e32 v55, 0xffff0000, v0
	v_lshlrev_b32_e32 v56, 16, v1
	v_and_b32_e32 v57, 0xffff0000, v1
	s_add_i32 s10, s9, 64
	ds_write_b128 v49, v[54:57] offset:14528
	v_lshlrev_b32_e32 v54, 16, v2
	v_and_b32_e32 v55, 0xffff0000, v2
	v_lshlrev_b32_e32 v56, 16, v3
	v_and_b32_e32 v57, 0xffff0000, v3
	s_cmp_ge_i32 s10, s21
	ds_write_b128 v49, v[54:57] offset:14544
	s_cbranch_scc1 .LBB0_464
	s_mov_b32 m0, s11
	v_mad_i64_i32 v[0:1], s[10:11], s10, v242, v[40:41]
	s_nop 0
	global_load_lds_dwordx4 v[0:1], off

.LBB0_480:
	s_lshl_b32 s8, s16, 4
	v_lshlrev_b32_e32 v0, 1, v42
	s_lshl_b32 s4, s92, 8
	v_and_b32_e32 v33, 14, v0
	s_or_b32 s4, s4, s8
	v_or_b32_e32 v0, s4, v33
	v_readlane_b32 s52, v252, 32
	v_ashrrev_i32_e32 v1, 31, v0
	v_readlane_b32 s56, v252, 36
	v_readlane_b32 s57, v252, 37
	v_mov_b32_e32 v200, v201
	v_cmp_gt_u32_e32 vcc, 16, v52
	v_lshl_add_u64 v[0:1], v[0:1], 2, s[56:57]
	global_load_dwordx2 v[42:43], v[0:1], off
	v_mov_b64_e32 v[0:1], v[200:201]
	v_mov_b64_e32 v[2:3], v[200:201]
	v_readlane_b32 s53, v252, 33
	v_readlane_b32 s54, v252, 34
	v_readlane_b32 s55, v252, 35
	v_readlane_b32 s58, v252, 38
	v_readlane_b32 s59, v252, 39
	v_readlane_b32 s60, v252, 40
	v_readlane_b32 s61, v252, 41
	v_readlane_b32 s62, v252, 42
	v_readlane_b32 s63, v252, 43
	v_readlane_b32 s64, v252, 44
	v_readlane_b32 s65, v252, 45
	v_readlane_b32 s66, v252, 46
	v_readlane_b32 s67, v252, 47
	s_and_saveexec_b64 s[4:5], vcc
	s_cbranch_execz .LBB0_482
	s_waitcnt vmcnt(0)
	s_ashr_i32 s10, s30, 6
	s_lshl_b32 s10, s10, 11
	s_add_u32 m0, s10, 0x8000
	s_add_i32 s10, s20, 0
	v_mad_i64_i32 v[0:1], s[10:11], s10, v242, v[40:41]
	s_nop 0
	global_load_lds_dwordx4 v[0:1], off
	s_ashr_i32 s10, s30, 6
	s_lshl_b32 s10, s10, 11
	s_add_u32 m0, s10, 0x8100
	s_add_i32 s10, s20, 8
	v_mad_i64_i32 v[0:1], s[10:11], s10, v242, v[40:41]
	s_nop 0
	global_load_lds_dwordx4 v[0:1], off
	s_ashr_i32 s10, s30, 6
	s_lshl_b32 s10, s10, 11
	s_add_u32 m0, s10, 0x8200
	s_add_i32 s10, s20, 16
	v_mad_i64_i32 v[0:1], s[10:11], s10, v242, v[40:41]
	s_nop 0
	global_load_lds_dwordx4 v[0:1], off
	s_ashr_i32 s10, s30, 6
	s_lshl_b32 s10, s10, 11
	s_add_u32 m0, s10, 0x8300
	s_add_i32 s10, s20, 24
	v_mad_i64_i32 v[0:1], s[10:11], s10, v242, v[40:41]
	s_nop 0
	global_load_lds_dwordx4 v[0:1], off
	s_ashr_i32 s10, s30, 6
	s_lshl_b32 s10, s10, 11
	s_add_u32 m0, s10, 0x8400
	s_add_i32 s10, s20, 32
	v_mad_i64_i32 v[0:1], s[10:11], s10, v242, v[40:41]
	s_nop 0
	global_load_lds_dwordx4 v[0:1], off
	s_ashr_i32 s10, s30, 6
	s_lshl_b32 s10, s10, 11
	s_add_u32 m0, s10, 0x8500
	s_add_i32 s10, s20, 40
	v_mad_i64_i32 v[0:1], s[10:11], s10, v242, v[40:41]
	s_nop 0
	global_load_lds_dwordx4 v[0:1], off
	s_ashr_i32 s10, s30, 6
	s_lshl_b32 s10, s10, 11
	s_add_u32 m0, s10, 0x8600
	s_add_i32 s10, s20, 48
	v_mad_i64_i32 v[0:1], s[10:11], s10, v242, v[40:41]
	s_nop 0
	global_load_lds_dwordx4 v[0:1], off
	s_ashr_i32 s10, s30, 6
	s_lshl_b32 s10, s10, 11
	s_add_u32 m0, s10, 0x8700
	s_add_i32 s10, s20, 56
	v_mad_i64_i32 v[0:1], s[10:11], s10, v242, v[40:41]
	s_nop 0
	global_load_lds_dwordx4 v[0:1], off

.LBB0_485:
	s_and_saveexec_b64 s[4:5], vcc
	s_cbranch_execz .LBB0_488
	s_add_i32 s8, s20, 64
	s_cmp_ge_i32 s8, s21
	s_cbranch_scc1 .Ls5p2_drain
	s_waitcnt vmcnt(7)
	s_branch .Ls5p2_go

.Ls5p2_go:
	s_lshr_b32 s9, s20, 3
	s_and_b32 s9, s9, 7
	s_lshl_b32 s9, s9, 8
	s_ashr_i32 m0, s30, 6
	s_lshl_b32 m0, m0, 11
	s_add_u32 s9, s9, m0
	s_add_u32 s9, s9, 0x8000
	v_lshl_add_u32 v48, v52, 4, s9
	ds_read_b128 v[0:3], v48
	s_waitcnt lgkmcnt(0)
	v_lshlrev_b32_e32 v48, 16, v0
	v_and_b32_e32 v49, 0xffff0000, v0
	v_lshlrev_b32_e32 v50, 16, v1
	v_and_b32_e32 v51, 0xffff0000, v1
	s_add_i32 s8, s20, 64
	ds_write_b128 v57, v[48:51] offset:14528
	v_lshlrev_b32_e32 v48, 16, v2
	v_and_b32_e32 v49, 0xffff0000, v2
	v_lshlrev_b32_e32 v50, 16, v3
	v_and_b32_e32 v51, 0xffff0000, v3
	s_cmp_ge_i32 s8, s21
	ds_write_b128 v57, v[48:51] offset:14544
	s_cbranch_scc1 .LBB0_488
	s_mov_b32 m0, s9
	v_mad_i64_i32 v[0:1], s[8:9], s8, v242, v[40:41]
	s_nop 0
	global_load_lds_dwordx4 v[0:1], off
.LBB0_488:
	s_or_b64 exec, exec, s[4:5]
	s_mov_b32 s4, 0
	v_mov_b32_e32 v48, v54
	ds_read_b128 v[132:135], v79 offset:0
	ds_read_b128 v[136:139], v79 offset:64
	ds_read_b128 v[140:143], v79 offset:128
	ds_read_b128 v[144:147], v79 offset:192
	ds_read_b128 v[148:151], v79 offset:256
	ds_read_b128 v[152:155], v79 offset:320
	ds_read_b128 v[156:159], v79 offset:384
	ds_read_b128 v[160:163], v79 offset:448
	ds_read_b128 v[164:167], v79 offset:16
	ds_read_b128 v[168:171], v79 offset:80
	ds_read_b128 v[172:175], v79 offset:144
	ds_read_b128 v[176:179], v79 offset:208
	ds_read_b128 v[180:183], v79 offset:272
	ds_read_b128 v[184:187], v79 offset:336
	ds_read_b128 v[188:191], v79 offset:400
	ds_read_b128 v[192:195], v79 offset:464
	s_waitcnt lgkmcnt(8)
	v_pk_fma_f32 v[84:85], v[36:37], v[132:133], 0 op_sel_hi:[1,0,0]
	v_pk_fma_f32 v[86:87], v[36:37], v[136:137], 0 op_sel_hi:[1,0,0]
	v_pk_fma_f32 v[88:89], v[36:37], v[140:141], 0 op_sel_hi:[1,0,0]
	v_pk_fma_f32 v[90:91], v[36:37], v[144:145], 0 op_sel_hi:[1,0,0]
	v_pk_fma_f32 v[92:93], v[36:37], v[148:149], 0 op_sel_hi:[1,0,0]
	v_pk_fma_f32 v[94:95], v[36:37], v[152:153], 0 op_sel_hi:[1,0,0]
	v_pk_fma_f32 v[96:97], v[36:37], v[156:157], 0 op_sel_hi:[1,0,0]
	v_pk_fma_f32 v[98:99], v[36:37], v[160:161], 0 op_sel_hi:[1,0,0]
	v_pk_fma_f32 v[84:85], v[28:29], v[132:133], v[84:85] op_sel:[0,1,0]
	v_pk_fma_f32 v[86:87], v[28:29], v[136:137], v[86:87] op_sel:[0,1,0]
	v_pk_fma_f32 v[88:89], v[28:29], v[140:141], v[88:89] op_sel:[0,1,0]
	v_pk_fma_f32 v[90:91], v[28:29], v[144:145], v[90:91] op_sel:[0,1,0]
	v_pk_fma_f32 v[92:93], v[28:29], v[148:149], v[92:93] op_sel:[0,1,0]
	v_pk_fma_f32 v[94:95], v[28:29], v[152:153], v[94:95] op_sel:[0,1,0]
	v_pk_fma_f32 v[96:97], v[28:29], v[156:157], v[96:97] op_sel:[0,1,0]
	v_pk_fma_f32 v[98:99], v[28:29], v[160:161], v[98:99] op_sel:[0,1,0]
	v_pk_fma_f32 v[84:85], v[24:25], v[134:135], v[84:85] op_sel_hi:[1,0,1]
	v_pk_fma_f32 v[86:87], v[24:25], v[138:139], v[86:87] op_sel_hi:[1,0,1]
	v_pk_fma_f32 v[88:89], v[24:25], v[142:143], v[88:89] op_sel_hi:[1,0,1]
	v_pk_fma_f32 v[90:91], v[24:25], v[146:147], v[90:91] op_sel_hi:[1,0,1]
	v_pk_fma_f32 v[92:93], v[24:25], v[150:151], v[92:93] op_sel_hi:[1,0,1]
	v_pk_fma_f32 v[94:95], v[24:25], v[154:155], v[94:95] op_sel_hi:[1,0,1]
	v_pk_fma_f32 v[96:97], v[24:25], v[158:159], v[96:97] op_sel_hi:[1,0,1]
	v_pk_fma_f32 v[98:99], v[24:25], v[162:163], v[98:99] op_sel_hi:[1,0,1]
	v_pk_fma_f32 v[84:85], v[26:27], v[134:135], v[84:85] op_sel:[0,1,0]
	v_pk_fma_f32 v[86:87], v[26:27], v[138:139], v[86:87] op_sel:[0,1,0]
	v_pk_fma_f32 v[88:89], v[26:27], v[142:143], v[88:89] op_sel:[0,1,0]
	v_pk_fma_f32 v[90:91], v[26:27], v[146:147], v[90:91] op_sel:[0,1,0]
	v_pk_fma_f32 v[92:93], v[26:27], v[150:151], v[92:93] op_sel:[0,1,0]
	v_pk_fma_f32 v[94:95], v[26:27], v[154:155], v[94:95] op_sel:[0,1,0]
	v_pk_fma_f32 v[96:97], v[26:27], v[158:159], v[96:97] op_sel:[0,1,0]
	v_pk_fma_f32 v[98:99], v[26:27], v[162:163], v[98:99] op_sel:[0,1,0]
	ds_read_b128 v[132:135], v79 offset:32
	ds_read_b128 v[136:139], v79 offset:96
	ds_read_b128 v[140:143], v79 offset:160
	ds_read_b128 v[144:147], v79 offset:224
	ds_read_b128 v[148:151], v79 offset:288
	ds_read_b128 v[152:155], v79 offset:352
	ds_read_b128 v[156:159], v79 offset:416
	ds_read_b128 v[160:163], v79 offset:480
	s_waitcnt lgkmcnt(8)
	v_pk_fma_f32 v[84:85], v[30:31], v[164:165], v[84:85] op_sel_hi:[1,0,1]
	v_pk_fma_f32 v[86:87], v[30:31], v[168:169], v[86:87] op_sel_hi:[1,0,1]
	v_pk_fma_f32 v[88:89], v[30:31], v[172:173], v[88:89] op_sel_hi:[1,0,1]
	v_pk_fma_f32 v[90:91], v[30:31], v[176:177], v[90:91] op_sel_hi:[1,0,1]
	v_pk_fma_f32 v[92:93], v[30:31], v[180:181], v[92:93] op_sel_hi:[1,0,1]
	v_pk_fma_f32 v[94:95], v[30:31], v[184:185], v[94:95] op_sel_hi:[1,0,1]
	v_pk_fma_f32 v[96:97], v[30:31], v[188:189], v[96:97] op_sel_hi:[1,0,1]
	v_pk_fma_f32 v[98:99], v[30:31], v[192:193], v[98:99] op_sel_hi:[1,0,1]
	v_pk_fma_f32 v[84:85], v[16:17], v[164:165], v[84:85] op_sel:[0,1,0]
	v_pk_fma_f32 v[86:87], v[16:17], v[168:169], v[86:87] op_sel:[0,1,0]
	v_pk_fma_f32 v[88:89], v[16:17], v[172:173], v[88:89] op_sel:[0,1,0]
	v_pk_fma_f32 v[90:91], v[16:17], v[176:177], v[90:91] op_sel:[0,1,0]
	v_pk_fma_f32 v[92:93], v[16:17], v[180:181], v[92:93] op_sel:[0,1,0]
	v_pk_fma_f32 v[94:95], v[16:17], v[184:185], v[94:95] op_sel:[0,1,0]
	v_pk_fma_f32 v[96:97], v[16:17], v[188:189], v[96:97] op_sel:[0,1,0]
	v_pk_fma_f32 v[98:99], v[16:17], v[192:193], v[98:99] op_sel:[0,1,0]
	v_pk_fma_f32 v[84:85], v[20:21], v[166:167], v[84:85] op_sel_hi:[1,0,1]
	v_pk_fma_f32 v[86:87], v[20:21], v[170:171], v[86:87] op_sel_hi:[1,0,1]
	v_pk_fma_f32 v[88:89], v[20:21], v[174:175], v[88:89] op_sel_hi:[1,0,1]
	v_pk_fma_f32 v[90:91], v[20:21], v[178:179], v[90:91] op_sel_hi:[1,0,1]
	v_pk_fma_f32 v[92:93], v[20:21], v[182:183], v[92:93] op_sel_hi:[1,0,1]
	v_pk_fma_f32 v[94:95], v[20:21], v[186:187], v[94:95] op_sel_hi:[1,0,1]
	v_pk_fma_f32 v[96:97], v[20:21], v[190:191], v[96:97] op_sel_hi:[1,0,1]
	v_pk_fma_f32 v[98:99], v[20:21], v[194:195], v[98:99] op_sel_hi:[1,0,1]
	v_pk_fma_f32 v[84:85], v[18:19], v[166:167], v[84:85] op_sel:[0,1,0]
	v_pk_fma_f32 v[86:87], v[18:19], v[170:171], v[86:87] op_sel:[0,1,0]
	v_pk_fma_f32 v[88:89], v[18:19], v[174:175], v[88:89] op_sel:[0,1,0]
	v_pk_fma_f32 v[90:91], v[18:19], v[178:179], v[90:91] op_sel:[0,1,0]
	v_pk_fma_f32 v[92:93], v[18:19], v[182:183], v[92:93] op_sel:[0,1,0]
	v_pk_fma_f32 v[94:95], v[18:19], v[186:187], v[94:95] op_sel:[0,1,0]
	v_pk_fma_f32 v[96:97], v[18:19], v[190:191], v[96:97] op_sel:[0,1,0]
	v_pk_fma_f32 v[98:99], v[18:19], v[194:195], v[98:99] op_sel:[0,1,0]
	ds_read_b128 v[164:167], v79 offset:48
	ds_read_b128 v[168:171], v79 offset:112
	ds_read_b128 v[172:175], v79 offset:176
	ds_read_b128 v[176:179], v79 offset:240
	ds_read_b128 v[180:183], v79 offset:304
	ds_read_b128 v[184:187], v79 offset:368
	ds_read_b128 v[188:191], v79 offset:432
	ds_read_b128 v[192:195], v79 offset:496
	s_waitcnt lgkmcnt(8)
	v_pk_fma_f32 v[84:85], v[22:23], v[132:133], v[84:85] op_sel_hi:[1,0,1]
	v_pk_fma_f32 v[86:87], v[22:23], v[136:137], v[86:87] op_sel_hi:[1,0,1]
	v_pk_fma_f32 v[88:89], v[22:23], v[140:141], v[88:89] op_sel_hi:[1,0,1]
	v_pk_fma_f32 v[90:91], v[22:23], v[144:145], v[90:91] op_sel_hi:[1,0,1]
	v_pk_fma_f32 v[92:93], v[22:23], v[148:149], v[92:93] op_sel_hi:[1,0,1]
	v_pk_fma_f32 v[94:95], v[22:23], v[152:153], v[94:95] op_sel_hi:[1,0,1]
	v_pk_fma_f32 v[96:97], v[22:23], v[156:157], v[96:97] op_sel_hi:[1,0,1]
	v_pk_fma_f32 v[98:99], v[22:23], v[160:161], v[98:99] op_sel_hi:[1,0,1]
	v_pk_fma_f32 v[84:85], v[8:9], v[132:133], v[84:85] op_sel:[0,1,0]
	v_pk_fma_f32 v[86:87], v[8:9], v[136:137], v[86:87] op_sel:[0,1,0]
	v_pk_fma_f32 v[88:89], v[8:9], v[140:141], v[88:89] op_sel:[0,1,0]
	v_pk_fma_f32 v[90:91], v[8:9], v[144:145], v[90:91] op_sel:[0,1,0]
	v_pk_fma_f32 v[92:93], v[8:9], v[148:149], v[92:93] op_sel:[0,1,0]
	v_pk_fma_f32 v[94:95], v[8:9], v[152:153], v[94:95] op_sel:[0,1,0]
	v_pk_fma_f32 v[96:97], v[8:9], v[156:157], v[96:97] op_sel:[0,1,0]
	v_pk_fma_f32 v[98:99], v[8:9], v[160:161], v[98:99] op_sel:[0,1,0]
	v_pk_fma_f32 v[84:85], v[12:13], v[134:135], v[84:85] op_sel_hi:[1,0,1]
	v_pk_fma_f32 v[86:87], v[12:13], v[138:139], v[86:87] op_sel_hi:[1,0,1]
	v_pk_fma_f32 v[88:89], v[12:13], v[142:143], v[88:89] op_sel_hi:[1,0,1]
	v_pk_fma_f32 v[90:91], v[12:13], v[146:147], v[90:91] op_sel_hi:[1,0,1]
	v_pk_fma_f32 v[92:93], v[12:13], v[150:151], v[92:93] op_sel_hi:[1,0,1]
	v_pk_fma_f32 v[94:95], v[12:13], v[154:155], v[94:95] op_sel_hi:[1,0,1]
	v_pk_fma_f32 v[96:97], v[12:13], v[158:159], v[96:97] op_sel_hi:[1,0,1]
	v_pk_fma_f32 v[98:99], v[12:13], v[162:163], v[98:99] op_sel_hi:[1,0,1]
	v_pk_fma_f32 v[84:85], v[10:11], v[134:135], v[84:85] op_sel:[0,1,0]
	v_pk_fma_f32 v[86:87], v[10:11], v[138:139], v[86:87] op_sel:[0,1,0]
	v_pk_fma_f32 v[88:89], v[10:11], v[142:143], v[88:89] op_sel:[0,1,0]
	v_pk_fma_f32 v[90:91], v[10:11], v[146:147], v[90:91] op_sel:[0,1,0]
	v_pk_fma_f32 v[92:93], v[10:11], v[150:151], v[92:93] op_sel:[0,1,0]
	v_pk_fma_f32 v[94:95], v[10:11], v[154:155], v[94:95] op_sel:[0,1,0]
	v_pk_fma_f32 v[96:97], v[10:11], v[158:159], v[96:97] op_sel:[0,1,0]
	v_pk_fma_f32 v[98:99], v[10:11], v[162:163], v[98:99] op_sel:[0,1,0]
	s_waitcnt lgkmcnt(0)
	v_pk_fma_f32 v[84:85], v[14:15], v[164:165], v[84:85] op_sel_hi:[1,0,1]
	v_pk_fma_f32 v[86:87], v[14:15], v[168:169], v[86:87] op_sel_hi:[1,0,1]
	v_pk_fma_f32 v[88:89], v[14:15], v[172:173], v[88:89] op_sel_hi:[1,0,1]
	v_pk_fma_f32 v[90:91], v[14:15], v[176:177], v[90:91] op_sel_hi:[1,0,1]
	v_pk_fma_f32 v[92:93], v[14:15], v[180:181], v[92:93] op_sel_hi:[1,0,1]
	v_pk_fma_f32 v[94:95], v[14:15], v[184:185], v[94:95] op_sel_hi:[1,0,1]
	v_pk_fma_f32 v[96:97], v[14:15], v[188:189], v[96:97] op_sel_hi:[1,0,1]
	v_pk_fma_f32 v[98:99], v[14:15], v[192:193], v[98:99] op_sel_hi:[1,0,1]
	v_pk_fma_f32 v[84:85], v[4:5], v[164:165], v[84:85] op_sel:[0,1,0]
	v_pk_fma_f32 v[86:87], v[4:5], v[168:169], v[86:87] op_sel:[0,1,0]
	v_pk_fma_f32 v[88:89], v[4:5], v[172:173], v[88:89] op_sel:[0,1,0]
	v_pk_fma_f32 v[90:91], v[4:5], v[176:177], v[90:91] op_sel:[0,1,0]
	v_pk_fma_f32 v[92:93], v[4:5], v[180:181], v[92:93] op_sel:[0,1,0]
	v_pk_fma_f32 v[94:95], v[4:5], v[184:185], v[94:95] op_sel:[0,1,0]
	v_pk_fma_f32 v[96:97], v[4:5], v[188:189], v[96:97] op_sel:[0,1,0]
	v_pk_fma_f32 v[98:99], v[4:5], v[192:193], v[98:99] op_sel:[0,1,0]
	v_pk_fma_f32 v[84:85], v[38:39], v[166:167], v[84:85] op_sel_hi:[1,0,1]
	v_pk_fma_f32 v[86:87], v[38:39], v[170:171], v[86:87] op_sel_hi:[1,0,1]
	v_pk_fma_f32 v[88:89], v[38:39], v[174:175], v[88:89] op_sel_hi:[1,0,1]
	v_pk_fma_f32 v[90:91], v[38:39], v[178:179], v[90:91] op_sel_hi:[1,0,1]
	v_pk_fma_f32 v[92:93], v[38:39], v[182:183], v[92:93] op_sel_hi:[1,0,1]
	v_pk_fma_f32 v[94:95], v[38:39], v[186:187], v[94:95] op_sel_hi:[1,0,1]
	v_pk_fma_f32 v[96:97], v[38:39], v[190:191], v[96:97] op_sel_hi:[1,0,1]
	v_pk_fma_f32 v[98:99], v[38:39], v[194:195], v[98:99] op_sel_hi:[1,0,1]
	v_pk_fma_f32 v[84:85], v[6:7], v[166:167], v[84:85] op_sel:[0,1,0]
	v_pk_fma_f32 v[86:87], v[6:7], v[170:171], v[86:87] op_sel:[0,1,0]
	v_pk_fma_f32 v[88:89], v[6:7], v[174:175], v[88:89] op_sel:[0,1,0]
	v_pk_fma_f32 v[90:91], v[6:7], v[178:179], v[90:91] op_sel:[0,1,0]
	v_pk_fma_f32 v[92:93], v[6:7], v[182:183], v[92:93] op_sel:[0,1,0]
	v_pk_fma_f32 v[94:95], v[6:7], v[186:187], v[94:95] op_sel:[0,1,0]
	v_pk_fma_f32 v[96:97], v[6:7], v[190:191], v[96:97] op_sel:[0,1,0]
	v_pk_fma_f32 v[98:99], v[6:7], v[194:195], v[98:99] op_sel:[0,1,0]
	v_fma_f32 v70, v32, v44, v84
	v_fma_f32 v71, v32, v45, v85
	v_fma_f32 v68, -v34, v45, v70
	v_fma_f32 v69, v34, v44, v71
	ds_write_b64 v54, v[68:69]
	v_fma_f32 v70, v32, v68, v86
	v_fma_f32 v71, v32, v69, v87
	v_fma_f32 v44, -v34, v69, v70
	v_fma_f32 v45, v34, v68, v71
	ds_write_b64 v54, v[44:45] offset:520
	v_fma_f32 v70, v32, v44, v88
	v_fma_f32 v71, v32, v45, v89
	v_fma_f32 v68, -v34, v45, v70
	v_fma_f32 v69, v34, v44, v71
	ds_write_b64 v54, v[68:69] offset:1040
	v_fma_f32 v70, v32, v68, v90
	v_fma_f32 v71, v32, v69, v91
	v_fma_f32 v44, -v34, v69, v70
	v_fma_f32 v45, v34, v68, v71
	ds_write_b64 v54, v[44:45] offset:1560
	v_fma_f32 v70, v32, v44, v92
	v_fma_f32 v71, v32, v45, v93
	v_fma_f32 v68, -v34, v45, v70
	v_fma_f32 v69, v34, v44, v71
	ds_write_b64 v54, v[68:69] offset:2080
	v_fma_f32 v70, v32, v68, v94
	v_fma_f32 v71, v32, v69, v95
	v_fma_f32 v44, -v34, v69, v70
	v_fma_f32 v45, v34, v68, v71
	ds_write_b64 v54, v[44:45] offset:2600
	v_fma_f32 v70, v32, v44, v96
	v_fma_f32 v71, v32, v45, v97
	v_fma_f32 v68, -v34, v45, v70
	v_fma_f32 v69, v34, v44, v71
	ds_write_b64 v54, v[68:69] offset:3120
	v_fma_f32 v70, v32, v68, v98
	v_fma_f32 v71, v32, v69, v99
	v_fma_f32 v44, -v34, v69, v70
	v_fma_f32 v45, v34, v68, v71
	ds_write_b64 v54, v[44:45] offset:3640
	ds_read2_b32 v[132:133], v76 offset0:0 offset1:4
	ds_read2_b32 v[134:135], v76 offset0:8 offset1:12
	ds_read2_b32 v[136:137], v76 offset0:16 offset1:20
	ds_read2_b32 v[138:139], v76 offset0:24 offset1:28
	ds_read2_b32 v[140:141], v76 offset0:32 offset1:36
	ds_read2_b32 v[142:143], v76 offset0:40 offset1:44
	ds_read2_b32 v[144:145], v76 offset0:48 offset1:52
	ds_read2_b32 v[146:147], v76 offset0:56 offset1:60
	ds_read2_b32 v[148:149], v76 offset0:64 offset1:68
	ds_read2_b32 v[150:151], v76 offset0:72 offset1:76
	ds_read2_b32 v[152:153], v76 offset0:80 offset1:84
	ds_read2_b32 v[154:155], v76 offset0:88 offset1:92
	ds_read2_b32 v[156:157], v76 offset0:96 offset1:100
	ds_read2_b32 v[158:159], v76 offset0:104 offset1:108
	ds_read2_b32 v[160:161], v76 offset0:112 offset1:116
	ds_read2_b32 v[162:163], v76 offset0:120 offset1:124
	s_waitcnt lgkmcnt(12)
	v_mfma_f32_16x16x4_f32 v[60:63], v132, v100, 0
	v_mfma_f32_16x16x4_f32 v[64:67], v133, v101, 0
	v_mfma_f32_16x16x4_f32 v[60:63], v134, v102, v[60:63]
	v_mfma_f32_16x16x4_f32 v[64:67], v135, v103, v[64:67]
	v_mfma_f32_16x16x4_f32 v[60:63], v136, v104, v[60:63]
	v_mfma_f32_16x16x4_f32 v[64:67], v137, v105, v[64:67]
	v_mfma_f32_16x16x4_f32 v[60:63], v138, v106, v[60:63]
	v_mfma_f32_16x16x4_f32 v[64:67], v139, v107, v[64:67]
	s_waitcnt lgkmcnt(0)
	v_mfma_f32_16x16x4_f32 v[60:63], v140, v108, v[60:63]
	v_mfma_f32_16x16x4_f32 v[64:67], v141, v109, v[64:67]
	v_mfma_f32_16x16x4_f32 v[60:63], v142, v110, v[60:63]
	v_mfma_f32_16x16x4_f32 v[64:67], v143, v111, v[64:67]
	v_mfma_f32_16x16x4_f32 v[60:63], v144, v112, v[60:63]
	v_mfma_f32_16x16x4_f32 v[64:67], v145, v113, v[64:67]
	v_mfma_f32_16x16x4_f32 v[60:63], v146, v114, v[60:63]
	v_mfma_f32_16x16x4_f32 v[64:67], v147, v115, v[64:67]
	v_mfma_f32_16x16x4_f32 v[60:63], v148, v116, v[60:63]
	v_mfma_f32_16x16x4_f32 v[64:67], v149, v117, v[64:67]
	v_mfma_f32_16x16x4_f32 v[60:63], v150, v118, v[60:63]
	v_mfma_f32_16x16x4_f32 v[64:67], v151, v119, v[64:67]
	v_mfma_f32_16x16x4_f32 v[60:63], v152, v120, v[60:63]
	v_mfma_f32_16x16x4_f32 v[64:67], v153, v121, v[64:67]
	v_mfma_f32_16x16x4_f32 v[60:63], v154, v122, v[60:63]
	v_mfma_f32_16x16x4_f32 v[64:67], v155, v123, v[64:67]
	v_mfma_f32_16x16x4_f32 v[60:63], v156, v124, v[60:63]
	v_mfma_f32_16x16x4_f32 v[64:67], v157, v125, v[64:67]
	v_mfma_f32_16x16x4_f32 v[60:63], v158, v126, v[60:63]
	v_mfma_f32_16x16x4_f32 v[64:67], v159, v127, v[64:67]
	v_mfma_f32_16x16x4_f32 v[60:63], v160, v128, v[60:63]
	v_mfma_f32_16x16x4_f32 v[64:67], v161, v129, v[64:67]
	v_mfma_f32_16x16x4_f32 v[60:63], v162, v130, v[60:63]
	v_mfma_f32_16x16x4_f32 v[64:67], v163, v131, v[64:67]
	s_nop 7
	s_nop 7
	v_pk_add_f32 v[60:61], v[60:61], v[64:65]
	v_pk_add_f32 v[62:63], v[62:63], v[66:67]
	s_nop 1
	ds_write_b32 v77, v60
	ds_write_b32 v77, v61 offset:64
	ds_write_b32 v77, v62 offset:128
	ds_write_b32 v77, v63 offset:192
	ds_read_b64 v[60:61], v78
	s_waitcnt lgkmcnt(0)
	v_mov_b32_e32 v49, v60
	v_mov_b32_e32 v48, v61
	ds_read_b64 v[50:51], v58 offset:14528
	s_waitcnt lgkmcnt(0)
	v_fma_f32 v49, v42, v50, v49
	v_mul_f32_e32 v50, 0x3d372713, v49
	v_mul_f32_e32 v50, v49, v50
	v_fma_f32 v50, v49, v50, v49
	v_mul_f32_e32 v50, 0x3f4c422a, v50
	v_cmp_nlt_f32_e64 s[4:5], |v50|, s24
	s_and_saveexec_b64 s[8:9], s[4:5]
	s_xor_b64 s[4:5], exec, s[8:9]
	s_cbranch_execz .LBB0_494
	v_add_f32_e64 v59, |v50|, |v50|
	v_mul_f32_e32 v60, 0x3fb8aa3b, v59
	v_rndne_f32_e32 v61, v60
	s_mov_b32 s8, 0x3fb8aa3b
	v_sub_f32_e32 v62, v60, v61
	v_fma_f32 v60, v59, s8, -v60
	v_fmac_f32_e32 v60, 0x32a5705f, v59
	v_add_f32_e32 v60, v62, v60
	v_cvt_i32_f32_e32 v61, v61
	v_exp_f32_e32 v60, v60
	s_mov_b32 s8, 0xc2ce8ed0
	v_cmp_ngt_f32_e64 s[8:9], s8, v59
	v_ldexp_f32 v60, v60, v61
	s_nop 0
	v_cndmask_b32_e64 v60, 0, v60, s[8:9]
	s_mov_b32 s8, 0x42b17218
	v_cmp_nlt_f32_e64 s[8:9], s8, v59
	s_nop 1
	v_cndmask_b32_e64 v59, v233, v60, s[8:9]
	v_add_f32_e32 v59, 1.0, v59
	v_rcp_f32_e32 v59, v59
	s_nop 0
	v_fma_f32 v59, v59, -2.0, 1.0
